# v2 plus: nt stores in the in-proj epilogue
# speedup vs baseline: 1.0370x; 1.0370x over previous
.LBB0_125:
	s_mul_i32 s16, s51, 0x160000
	v_lshl_or_b32 v164, s46, 8, v158
	s_mul_hi_i32 s17, s51, 0x160000
	s_add_u32 s16, s31, s16
	v_ashrrev_i32_e32 v165, 31, v164
	s_addc_u32 s17, s33, s17
	v_lshl_add_u64 v[166:167], s[16:17], 0, v[132:133]
	v_lshlrev_b64 v[164:165], 1, v[164:165]
	v_lshl_add_u64 v[166:167], v[166:167], 0, v[164:165]
	v_cvt_pk_bf16_f32 v126, v126, v127
	v_cvt_pk_bf16_f32 v127, v128, v129
	v_cvt_pk_bf16_f32 v128, v122, v123
	v_cvt_pk_bf16_f32 v129, v124, v125
	global_store_dwordx4 v[166:167], v[126:129], off nt
	v_cvt_pk_bf16_f32 v114, v114, v115
	v_cvt_pk_bf16_f32 v115, v116, v117
	v_cvt_pk_bf16_f32 v116, v106, v107
	v_lshl_add_u64 v[106:107], s[16:17], 0, v[134:135]
	v_cvt_pk_bf16_f32 v117, v108, v109
	global_store_dwordx4 v[166:167], v[114:117], off offset:256 nt
	s_nop 1
	v_lshl_add_u64 v[114:115], v[106:107], 0, v[164:165]
	v_cvt_pk_bf16_f32 v106, v118, v119
	v_cvt_pk_bf16_f32 v107, v120, v121
	v_cvt_pk_bf16_f32 v108, v110, v111
	v_cvt_pk_bf16_f32 v109, v112, v113
	global_store_dwordx4 v[114:115], v[106:109], off nt
	v_cvt_pk_bf16_f32 v98, v98, v99
	v_cvt_pk_bf16_f32 v99, v100, v101
	v_cvt_pk_bf16_f32 v100, v90, v91
	v_lshl_add_u64 v[90:91], s[16:17], 0, v[136:137]
	v_cvt_pk_bf16_f32 v101, v92, v93
	global_store_dwordx4 v[114:115], v[98:101], off offset:256 nt
	s_nop 1
	v_lshl_add_u64 v[98:99], v[90:91], 0, v[164:165]
	v_cvt_pk_bf16_f32 v90, v102, v103
	v_cvt_pk_bf16_f32 v91, v104, v105
	v_cvt_pk_bf16_f32 v92, v94, v95
	v_cvt_pk_bf16_f32 v93, v96, v97
	global_store_dwordx4 v[98:99], v[90:93], off nt
	v_cvt_pk_bf16_f32 v82, v82, v83
	v_cvt_pk_bf16_f32 v83, v84, v85
	v_cvt_pk_bf16_f32 v84, v74, v75
	v_lshl_add_u64 v[74:75], s[16:17], 0, v[138:139]
	v_cvt_pk_bf16_f32 v85, v76, v77
	global_store_dwordx4 v[98:99], v[82:85], off offset:256 nt
	s_nop 1
	v_lshl_add_u64 v[82:83], v[74:75], 0, v[164:165]
	v_cvt_pk_bf16_f32 v74, v86, v87
	v_cvt_pk_bf16_f32 v75, v88, v89
	v_cvt_pk_bf16_f32 v76, v78, v79
	v_cvt_pk_bf16_f32 v77, v80, v81
	global_store_dwordx4 v[82:83], v[74:77], off nt
	v_cvt_pk_bf16_f32 v70, v70, v71
	v_cvt_pk_bf16_f32 v71, v72, v73
	v_cvt_pk_bf16_f32 v72, v66, v67
	v_lshl_add_u64 v[66:67], s[16:17], 0, v[140:141]
	v_lshl_add_u64 v[66:67], v[66:67], 0, v[164:165]
	v_cvt_pk_bf16_f32 v73, v68, v69
	global_store_dwordx4 v[82:83], v[70:73], off offset:256 nt
	v_cvt_pk_bf16_f32 v62, v62, v63
	v_cvt_pk_bf16_f32 v63, v64, v65
	v_cvt_pk_bf16_f32 v64, v58, v59
	v_cvt_pk_bf16_f32 v65, v60, v61
	global_store_dwordx4 v[66:67], v[62:65], off nt
	v_cvt_pk_bf16_f32 v50, v50, v51
	v_cvt_pk_bf16_f32 v51, v52, v53
	v_cvt_pk_bf16_f32 v52, v42, v43
	v_lshl_add_u64 v[42:43], s[16:17], 0, v[142:143]
	v_cvt_pk_bf16_f32 v53, v44, v45
	global_store_dwordx4 v[66:67], v[50:53], off offset:256 nt
	s_nop 1
	v_lshl_add_u64 v[50:51], v[42:43], 0, v[164:165]
	v_cvt_pk_bf16_f32 v42, v54, v55
	v_cvt_pk_bf16_f32 v43, v56, v57
	v_cvt_pk_bf16_f32 v44, v46, v47
	v_cvt_pk_bf16_f32 v45, v48, v49
	global_store_dwordx4 v[50:51], v[42:45], off nt
	v_cvt_pk_bf16_f32 v34, v34, v35
	v_cvt_pk_bf16_f32 v35, v36, v37
	v_cvt_pk_bf16_f32 v36, v26, v27
	v_lshl_add_u64 v[26:27], s[16:17], 0, v[144:145]
	v_cvt_pk_bf16_f32 v37, v28, v29
	global_store_dwordx4 v[50:51], v[34:37], off offset:256 nt
	s_nop 1
	v_lshl_add_u64 v[34:35], v[26:27], 0, v[164:165]
	v_cvt_pk_bf16_f32 v26, v38, v39
	v_cvt_pk_bf16_f32 v27, v40, v41
	v_cvt_pk_bf16_f32 v28, v30, v31
	v_cvt_pk_bf16_f32 v29, v32, v33
	global_store_dwordx4 v[34:35], v[26:29], off nt
	v_cvt_pk_bf16_f32 v18, v18, v19
	v_cvt_pk_bf16_f32 v19, v20, v21
	v_cvt_pk_bf16_f32 v20, v10, v11
	v_lshl_add_u64 v[10:11], s[16:17], 0, v[146:147]
	v_cvt_pk_bf16_f32 v21, v12, v13
	global_store_dwordx4 v[34:35], v[18:21], off offset:256 nt
	s_nop 1
	v_lshl_add_u64 v[18:19], v[10:11], 0, v[164:165]
	v_cvt_pk_bf16_f32 v10, v22, v23
	v_cvt_pk_bf16_f32 v11, v24, v25
	v_cvt_pk_bf16_f32 v12, v14, v15
	v_cvt_pk_bf16_f32 v13, v16, v17
	global_store_dwordx4 v[18:19], v[10:13], off nt
	v_cvt_pk_bf16_f32 v6, v6, v7
	v_cvt_pk_bf16_f32 v7, v8, v9
	v_cvt_pk_bf16_f32 v8, v2, v3
	v_cvt_pk_bf16_f32 v9, v4, v5
	global_store_dwordx4 v[18:19], v[6:9], off offset:256 nt
	s_andn2_b64 vcc, exec, s[4:5]
	s_mov_b64 s[4:5], -1
	s_cbranch_vccnz .LBB0_117
	s_branch .LBB0_129

.LBB0_127:
	v_lshl_add_u32 v168, s51, 8, v130
	v_ashrrev_i32_e32 v169, 31, v168
	v_lshl_add_u32 v152, s46, 7, v159
	v_lshlrev_b64 v[164:165], 11, v[168:169]
	v_lshl_add_u64 v[164:165], s[2:3], 0, v[164:165]
	v_lshlrev_b64 v[170:171], 1, v[152:153]
	v_lshl_add_u64 v[172:173], v[164:165], 0, v[170:171]
	v_mul_f32_e32 v152, v126, v114
	v_mul_f32_e32 v164, v127, v115
	v_cvt_pk_bf16_f32 v164, v152, v164
	v_mul_f32_e32 v152, v128, v116
	v_mul_f32_e32 v165, v129, v117
	v_cvt_pk_bf16_f32 v165, v152, v165
	v_mul_f32_e32 v152, v122, v106
	v_mul_f32_e32 v166, v123, v107
	v_mul_f32_e32 v167, v125, v109
	v_cvt_pk_bf16_f32 v166, v152, v166
	v_mul_f32_e32 v152, v124, v108
	v_cvt_pk_bf16_f32 v167, v152, v167
	global_store_dwordx4 v[172:173], v[164:167], off nt
	v_mul_f32_e32 v152, v118, v98
	s_nop 0
	v_or_b32_e32 v164, 16, v168
	v_ashrrev_i32_e32 v165, 31, v164
	v_lshlrev_b64 v[164:165], 11, v[164:165]
	v_lshl_add_u64 v[164:165], s[2:3], 0, v[164:165]
	v_lshl_add_u64 v[174:175], v[164:165], 0, v[170:171]
	v_mul_f32_e32 v164, v119, v99
	v_cvt_pk_bf16_f32 v164, v152, v164
	v_mul_f32_e32 v152, v120, v100
	v_mul_f32_e32 v165, v121, v101
	v_cvt_pk_bf16_f32 v165, v152, v165
	v_mul_f32_e32 v152, v110, v90
	v_mul_f32_e32 v166, v111, v91
	v_mul_f32_e32 v167, v113, v93
	v_cvt_pk_bf16_f32 v166, v152, v166
	v_mul_f32_e32 v152, v112, v92
	v_cvt_pk_bf16_f32 v167, v152, v167
	global_store_dwordx4 v[174:175], v[164:167], off nt
	v_mul_f32_e32 v152, v102, v82
	s_nop 0
	v_or_b32_e32 v164, 32, v168
	v_ashrrev_i32_e32 v165, 31, v164
	v_lshlrev_b64 v[164:165], 11, v[164:165]
	v_lshl_add_u64 v[164:165], s[2:3], 0, v[164:165]
	v_lshl_add_u64 v[174:175], v[164:165], 0, v[170:171]
	v_mul_f32_e32 v164, v103, v83
	v_cvt_pk_bf16_f32 v164, v152, v164
	v_mul_f32_e32 v152, v104, v84
	v_mul_f32_e32 v165, v105, v85
	v_cvt_pk_bf16_f32 v165, v152, v165
	v_mul_f32_e32 v152, v94, v74
	v_mul_f32_e32 v166, v95, v75
	v_mul_f32_e32 v167, v97, v77
	v_cvt_pk_bf16_f32 v166, v152, v166
	v_mul_f32_e32 v152, v96, v76
	v_cvt_pk_bf16_f32 v167, v152, v167
	global_store_dwordx4 v[174:175], v[164:167], off nt
	v_mul_f32_e32 v152, v86, v70
	s_nop 0
	v_or_b32_e32 v164, 48, v168
	v_ashrrev_i32_e32 v165, 31, v164
	v_lshlrev_b64 v[164:165], 11, v[164:165]
	v_lshl_add_u64 v[164:165], s[2:3], 0, v[164:165]
	v_lshl_add_u64 v[168:169], v[164:165], 0, v[170:171]
	v_mul_f32_e32 v164, v87, v71
	v_cvt_pk_bf16_f32 v164, v152, v164
	v_mul_f32_e32 v152, v88, v72
	v_mul_f32_e32 v165, v89, v73
	v_cvt_pk_bf16_f32 v165, v152, v165
	v_mul_f32_e32 v152, v78, v66
	v_mul_f32_e32 v166, v79, v67
	v_cvt_pk_bf16_f32 v166, v152, v166
	v_mul_f32_e32 v152, v80, v68
	v_mul_f32_e32 v167, v81, v69
	v_cvt_pk_bf16_f32 v167, v152, v167
	global_store_dwordx4 v[168:169], v[164:167], off nt
	v_mul_f32_e32 v152, v62, v50
	v_add_co_u32_e32 v168, vcc, s29, v172
	v_mul_f32_e32 v164, v63, v51
	v_cvt_pk_bf16_f32 v164, v152, v164
	v_mul_f32_e32 v152, v64, v52
	v_mul_f32_e32 v165, v65, v53
	v_cvt_pk_bf16_f32 v165, v152, v165
	v_mul_f32_e32 v152, v58, v42
	v_mul_f32_e32 v166, v59, v43
	v_cvt_pk_bf16_f32 v166, v152, v166
	v_mul_f32_e32 v152, v60, v44
	v_mul_f32_e32 v167, v61, v45
	v_addc_co_u32_e32 v169, vcc, 0, v173, vcc
	v_cvt_pk_bf16_f32 v167, v152, v167
	global_store_dwordx4 v[168:169], v[164:167], off nt
	v_mul_f32_e32 v152, v54, v34
	v_add_co_u32_e32 v168, vcc, s44, v172
	v_mul_f32_e32 v164, v55, v35
	v_cvt_pk_bf16_f32 v164, v152, v164
	v_mul_f32_e32 v152, v56, v36
	v_mul_f32_e32 v165, v57, v37
	v_cvt_pk_bf16_f32 v165, v152, v165
	v_mul_f32_e32 v152, v46, v26
	v_mul_f32_e32 v166, v47, v27
	v_cvt_pk_bf16_f32 v166, v152, v166
	v_mul_f32_e32 v152, v48, v28
	v_mul_f32_e32 v167, v49, v29
	v_addc_co_u32_e32 v169, vcc, 0, v173, vcc
	v_cvt_pk_bf16_f32 v167, v152, v167
	global_store_dwordx4 v[168:169], v[164:167], off nt
	v_mul_f32_e32 v152, v38, v18
	v_add_co_u32_e32 v168, vcc, s45, v172
	v_mul_f32_e32 v164, v39, v19
	v_cvt_pk_bf16_f32 v164, v152, v164
	v_mul_f32_e32 v152, v40, v20
	v_mul_f32_e32 v165, v41, v21
	v_cvt_pk_bf16_f32 v165, v152, v165
	v_mul_f32_e32 v152, v30, v10
	v_mul_f32_e32 v166, v31, v11
	v_cvt_pk_bf16_f32 v166, v152, v166
	v_mul_f32_e32 v152, v32, v12
	v_mul_f32_e32 v167, v33, v13
	v_addc_co_u32_e32 v169, vcc, 0, v173, vcc
	v_cvt_pk_bf16_f32 v167, v152, v167
	global_store_dwordx4 v[168:169], v[164:167], off nt
	v_mul_f32_e32 v152, v22, v6
	v_add_co_u32_e32 v168, vcc, 0x58000, v172
	v_mul_f32_e32 v164, v23, v7
	v_cvt_pk_bf16_f32 v164, v152, v164
	v_mul_f32_e32 v152, v24, v8
	v_mul_f32_e32 v165, v25, v9
	v_cvt_pk_bf16_f32 v165, v152, v165
	v_mul_f32_e32 v152, v14, v2
	v_mul_f32_e32 v166, v15, v3
	v_mul_f32_e32 v167, v17, v5
	v_addc_co_u32_e32 v169, vcc, 0, v173, vcc
	v_cvt_pk_bf16_f32 v166, v152, v166
	v_mul_f32_e32 v152, v16, v4
	v_cvt_pk_bf16_f32 v167, v152, v167
	global_store_dwordx4 v[168:169], v[164:167], off nt
	s_cbranch_execz .LBB0_125
